# attention partner-wave skew after the pair barrier raised from 128 to 192 cycles (s_sleep 3)
# speedup vs baseline: 1.0059x; 1.0059x over previous
.Latt_even_entry:
	s_waitcnt vmcnt(0) lgkmcnt(0)
	s_barrier
	s_bitcmp1_b32 s97, 8
	s_cbranch_scc0 .Latt_no_skew
	s_sleep 3
